# MLA fast path: K-fragment ds_reads first with counted lgkmcnt, next-tile LDS-DMA issue interleaved into QK MFMA chain
# speedup vs baseline: 1.0271x; 1.0046x over previous
; template <bool DIFF>
; DI void attn_phase(const AttnArgs& a, char* lds) {
;     ...
;     for (int t = t_beg; t < t_end; ++t) {
;       const char* sb = lds + (t & 1) * STAGE;
;       char* nb = lds + ((t + 1) & 1) * STAGE;
;       const bool nxt = t + 1 < t_end;
;       const int4 tinfo = *(const int4*)(ttab + 4 * t);
;       const int kcmin = __builtin_amdgcn_readfirstlane(tinfo.x), kcmax = __builtin_amdgcn_readfirstlane(tinfo.y);
;       bool skip = kcmin > wqcmax;
;       if (DIFF) {
;         const int tpmin = __builtin_amdgcn_readfirstlane(tinfo.z), tpmax = __builtin_amdgcn_readfirstlane(tinfo.w);
;         const int dist = max(0, max(wpmin - tpmax, tpmin - wpmax));
;         skip = skip || (slope2 * (float)dist > lim2);
;       }
;       const bool needmask = kcmax > wqcmin;
;       if (nxt) {
;         const int t2 = tid_pinned();
;         const u32 kofs = KOFS(t2), vofs = VOFS(t2);
;         const u32 ko2 = kofs + (u32)(t + 1) * 64u * (u32)a.ldk;
; #pragma unroll
;         for (int i = 0; i < NKR; ++i) GLDS16(a.K + ko2 + i * 64, nb + wave * 1024 + 8192 * i);
;         const u32 vo2 = vofs + (u32)(t + 1) * (u32)(DV * 64);
; #pragma unroll
;         for (int i = 0; i < NVR; ++i) GLDS16(a.VT + vo2 + i * 4096, nb + KBYTES + wave * 1024 + 8192 * i);
;         if (wave == 0) { const int l4 = (t + 1) * 64 + (t2 & 63); GLDS4(a.pos + l4, nb + KBYTES + VBYTES); GLDS4(a.posf + l4, nb + KBYTES + VBYTES + 256); }
;       }
;       int uft = usefix_i; asm volatile("" : "+v"(uft)); uft = __builtin_amdgcn_readfirstlane(uft);
;       if (!DIFF && uft != 0 && !skip) {
;         const int* pki = (const int*)(sb + KBYTES + VBYTES);
;         const int l2 = tid_pinned() & 63, l31b = l2 & 31, g2 = l2 >> 5;
;         const int prow = (((l31b >> 4) & 1) << 4) | (((l31b >> 2) & 1) << 3) | (((l31b >> 3) & 1) << 2) | (l31b & 3);
;         const int kx = g2 ^ ((prow >> 1) & 7);
;         const int koffb = prow * 128;
;         const int vx = g2 ^ ((l31b >> 1) & 7);
;         const int voffb = KBYTES + l31b * 128;
;         bf16x8 kf[NDS];
; #pragma unroll
;         for (int ds = 0; ds < NDS; ++ds) kf[ds] = *(const bf16x8*)(sb + koffb + (ds >> 2) * 8192 + ((((ds & 3) * 2) ^ kx) << 4));
;         f32x16 s0, s1;
;         __builtin_amdgcn_s_setprio(1);
;         s0 = MFMA(kf[0], qf[0], negm);
; #pragma unroll
;         for (int ds = 1; ds < NDS; ++ds) s0 = MFMA(kf[ds], qf[ds], s0);
.LBB0_376:
	s_add_i32 s10, s7, -4
	v_mov_b32_e32 v0, s10
	ds_read_b64 v[2:3], v0
	s_add_i32 s53, s22, 1
	s_bitcmp1_b32 s53, 0
	s_cselect_b32 s85, 0xa200, 0
	s_add_i32 s88, s85, s59
	s_waitcnt lgkmcnt(0)
	v_readfirstlane_b32 s11, v2
	v_readfirstlane_b32 s10, v3
	s_bitcmp1_b32 s22, 0
	v_mov_b32_e32 v0, v214
	s_cselect_b32 s63, 0xa200, 0
	s_cmp_gt_i32 s11, s1
	s_nop 0
	s_cselect_b64 s[74:75], -1, 0
	v_readfirstlane_b32 s22, v0
	s_cmp_eq_u32 s22, 0
	s_cselect_b64 s[86:87], -1, 0
	v_cmp_gt_i32_e64 s[10:11], s10, v213
	s_or_b64 s[86:87], s[86:87], s[74:75]
	s_and_b64 vcc, exec, s[86:87]
	v_cndmask_b32_e64 v0, 0, 1, s[10:11]
	v_cmp_ne_u32_e64 s[10:11], 1, v0
	s_cbranch_vccnz .Lmla_slow
	v_mov_b32_e32 v0, v208
	s_nop 0
	v_lshlrev_b32_e32 v2, 1, v0
	v_lshrrev_b32_e32 v3, 1, v0
	v_and_b32_e32 v2, 8, v2
	v_and_b32_e32 v3, 4, v3
	v_and_b32_e32 v4, 19, v0
	v_or3_b32 v2, v2, v4, v3
	v_bfe_u32 v15, v0, 5, 1
	v_lshrrev_b32_e32 v3, 1, v2
	v_bitop3_b32 v3, v3, v15, 7 bitop3:0x6c
	v_lshl_add_u32 v2, v2, 7, s63
	v_lshlrev_b32_e32 v3, 4, v3
	v_add_u32_e32 v172, v2, v3
	v_xad_u32 v176, v3, 32, v2
	v_xad_u32 v180, v3, 64, v2
	v_xad_u32 v226, v3, s82, v2
	ds_read_b128 v[2:5], v172
	ds_read_b128 v[84:87], v176
	ds_read_b128 v[10:13], v180
	ds_read_b128 v[164:167], v226
	ds_read_b128 v[6:9], v172 offset:8192
	ds_read_b128 v[92:95], v176 offset:8192
	ds_read_b128 v[80:83], v180 offset:8192
	ds_read_b128 v[168:171], v226 offset:8192
	ds_read_b128 v[88:91], v172 offset:16384
	ds_read_b128 v[160:163], v176 offset:16384
	ds_read_b128 v[218:221], v180 offset:16384
	ds_read_b128 v[222:225], v226 offset:16384
	v_lshrrev_b32_e32 v14, 5, v0
	v_bfe_u32 v96, v0, 1, 3
	v_lshlrev_b32_e32 v0, 7, v0
	v_and_b32_e32 v0, 0xf80, v0
	v_bitop3_b32 v14, v14, v96, 1 bitop3:0x6c
	v_lshrrev_b32_e32 v228, 4, v208
	v_xor_b32_e32 v228, v228, v208
	v_ashrrev_i32_e32 v230, 3, v208
	v_lshlrev_b32_e32 v228, 3, v228
	v_and_b32_e32 v231, 56, v228
	v_add_u32_e32 v228, s52, v230
	v_mul_lo_u32 v228, v228, s76
	v_mov_b32_e32 v229, 0
	v_add_u32_e32 v228, s4, v228
	v_or_b32_e32 v228, v228, v231
	v_lshl_add_u64 v[232:233], v[228:229], 1, s[14:15]
	v_lshl_or_b32 v228, v230, 6, v231
	v_add_u32_e32 v228, s5, v228
	v_lshl_add_u64 v[234:235], v[232:233], 0, s[16:17]
	v_lshl_add_u64 v[236:237], v[232:233], 0, s[18:19]
	v_lshl_add_u64 v[238:239], v[228:229], 1, s[40:41]
	v_lshl_add_u64 v[240:241], v[238:239], 0, s[68:69]
	v_and_b32_e32 v242, 63, v208
	v_add_u32_e32 v242, s52, v242
	v_ashrrev_i32_e32 v243, 31, v242
	v_lshlrev_b64 v[242:243], 2, v[242:243]
	v_lshl_add_u64 v[244:245], s[48:49], 0, v[242:243]
	v_lshl_add_u64 v[242:243], s[38:39], 0, v[242:243]
	s_add_i32 s89, s88, 0x2000
	s_add_i32 s90, s88, 0x4000
	s_add_i32 s91, s88, 0x6000
	s_add_i32 s32, s88, 0x8000
	s_cmp_ge_i32 s53, s0
	s_cselect_b64 vcc, -1, 0
	s_mov_b32 m0, s88
	s_setprio 1
	s_waitcnt lgkmcnt(11)
	v_mfma_f32_32x32x16_bf16 v[96:111], v[2:5], v[112:115], 0
	s_setprio 0
	s_cbranch_vccnz .Lmla_nd1
	global_load_lds_dwordx4 v[232:233], off
.Lmla_nd1:
	s_waitcnt lgkmcnt(10)
	v_mfma_f32_32x32x16_bf16 v[96:111], v[84:87], v[116:119], v[96:111]
	v_add_u32_e32 v0, s63, v0
	v_lshlrev_b32_e32 v14, 4, v14
	v_add_u32_e32 v2, v0, v14
	s_mov_b32 m0, s89
	s_waitcnt lgkmcnt(9)
	v_mfma_f32_32x32x16_bf16 v[96:111], v[10:13], v[120:123], v[96:111]
	s_cbranch_vccnz .Lmla_nd2
	global_load_lds_dwordx4 v[234:235], off
.Lmla_nd2:
	s_waitcnt lgkmcnt(8)
	v_mfma_f32_32x32x16_bf16 v[96:111], v[164:167], v[124:127], v[96:111]
	s_mov_b32 m0, s90
	s_waitcnt lgkmcnt(7)
	v_mfma_f32_32x32x16_bf16 v[96:111], v[6:9], v[128:131], v[96:111]
	s_cbranch_vccnz .Lmla_nd3
	global_load_lds_dwordx4 v[236:237], off
; #define MFMA(a, b, c) __builtin_amdgcn_mfma_f32_32x32x16_bf16((a), (b), (c), 0, 0, 0)
; #define GLDS16(g, l) __builtin_amdgcn_global_load_lds((const unsigned*)(g), (unsigned*)(l), 16, 0, 0)
; template <bool DIFF>
; DI void attn_phase(const AttnArgs& a, char* lds) {
;     ...
; #pragma unroll
;         for (int i = 0; i < NKR; ++i) GLDS16(a.K + ko2 + i * 64, nb + wave * 1024 + 8192 * i);
;         const u32 vo2 = vofs + (u32)(t + 1) * (u32)(DV * 64);
; #pragma unroll
;         for (int i = 0; i < NVR; ++i) GLDS16(a.VT + vo2 + i * 4096, nb + KBYTES + wave * 1024 + 8192 * i);
;         if (wave == 0) { const int l4 = (t + 1) * 64 + (t2 & 63); GLDS4(a.pos + l4, nb + KBYTES + VBYTES); GLDS4(a.posf + l4, nb + KBYTES + VBYTES + 256); }
;       }
;       int uft = usefix_i; asm volatile("" : "+v"(uft)); uft = __builtin_amdgcn_readfirstlane(uft);
;       if (!DIFF && uft != 0 && !skip) {
;         const int* pki = (const int*)(sb + KBYTES + VBYTES);
;         const int l2 = tid_pinned() & 63, l31b = l2 & 31, g2 = l2 >> 5;
;         const int prow = (((l31b >> 4) & 1) << 4) | (((l31b >> 2) & 1) << 3) | (((l31b >> 3) & 1) << 2) | (l31b & 3);
;         const int kx = g2 ^ ((prow >> 1) & 7);
;         const int koffb = prow * 128;
;         const int vx = g2 ^ ((l31b >> 1) & 7);
;         const int voffb = KBYTES + l31b * 128;
;         bf16x8 kf[NDS];
; #pragma unroll
;         for (int ds = 0; ds < NDS; ++ds) kf[ds] = *(const bf16x8*)(sb + koffb + (ds >> 2) * 8192 + ((((ds & 3) * 2) ^ kx) << 4));
;         f32x16 s0, s1;
;         __builtin_amdgcn_s_setprio(1);
;         s0 = MFMA(kf[0], qf[0], negm);
; #pragma unroll
;         for (int ds = 1; ds < NDS; ++ds) s0 = MFMA(kf[ds], qf[ds], s0);
;         __builtin_amdgcn_s_setprio(0);
; #pragma unroll
;         for (int ds = 0; ds < NDS; ++ds) kf[ds] = *(const bf16x8*)(sb + koffb + 4096 + (ds >> 2) * 8192 + ((((ds & 3) * 2) ^ kx) << 4));
;         bf16x8 vf[2][NM];
; #pragma unroll
;         for (int m = 0; m < NM; ++m) vf[0][m] = *(const bf16x8*)(sb + voffb + m * 4096 + ((0 ^ vx) << 4));
;         __builtin_amdgcn_sched_barrier(0);
;         if (needmask) {
; #pragma unroll
;           for (int r = 0; r < 16; ++r) {
;             const int kl = (r < 8) ? (8 * g2 + r) : (16 + 8 * g2 + (r - 8));
;             if ((pki[kl] >> 6) > (((int)qposf) >> 6)) s0[r] = -__builtin_inff();
;           }
;         }
.Lmla_nd3:
	s_waitcnt lgkmcnt(6)
	v_mfma_f32_32x32x16_bf16 v[96:111], v[92:95], v[132:135], v[96:111]
	s_mov_b32 m0, s91
	s_waitcnt lgkmcnt(5)
	v_mfma_f32_32x32x16_bf16 v[96:111], v[80:83], v[136:139], v[96:111]
	s_cbranch_vccnz .Lmla_nd4
	global_load_lds_dwordx4 v[238:239], off
.Lmla_nd4:
	s_waitcnt lgkmcnt(4)
	v_mfma_f32_32x32x16_bf16 v[96:111], v[168:171], v[140:143], v[96:111]
	ds_read_b128 v[80:83], v172 offset:4096
	ds_read_b128 v[192:195], v172 offset:12288
	ds_read_b128 v[200:203], v180 offset:4096
	ds_read_b128 v[168:171], v180 offset:12288
	ds_read_b128 v[204:207], v176 offset:4096
	ds_read_b128 v[172:175], v172 offset:20480
	ds_read_b128 v[184:187], v176 offset:12288
	ds_read_b128 v[176:179], v176 offset:20480
	ds_read_b128 v[196:199], v226 offset:4096
	ds_read_b128 v[180:183], v180 offset:20480
	ds_read_b128 v[188:191], v226 offset:12288
	ds_read_b128 v[164:167], v226 offset:20480
	s_mov_b32 m0, s32
	s_waitcnt lgkmcnt(15)
	v_mfma_f32_32x32x16_bf16 v[96:111], v[88:91], v[144:147], v[96:111]
	s_cbranch_vccnz .Lmla_nd5
	global_load_lds_dwordx4 v[240:241], off
.Lmla_nd5:
	s_waitcnt lgkmcnt(14)
	v_mfma_f32_32x32x16_bf16 v[96:111], v[160:163], v[148:151], v[96:111]
	ds_read_b128 v[160:163], v2 offset:24576
	ds_read_b128 v[10:13], v2 offset:28672
	ds_read_b128 v[6:9], v2 offset:32768
	ds_read_b128 v[2:5], v2 offset:36864
	s_waitcnt lgkmcnt(15)
	v_mfma_f32_32x32x16_bf16 v[96:111], v[218:221], v[152:155], v[96:111]
	s_cbranch_vccnz .Lmla_nd6
	s_and_b64 vcc, exec, s[8:9]
	s_cbranch_vccnz .Lmla_nd6
	s_add_i32 m0, s85, 0xa000
	s_nop 0
	global_load_lds_dword v[242:243], off
	s_add_i32 m0, s85, 0xa100
	s_nop 0
	global_load_lds_dword v[244:245], off
.Lmla_nd6:
	s_waitcnt lgkmcnt(15)
	v_mfma_f32_32x32x16_bf16 v[96:111], v[222:225], v[156:159], v[96:111]
	s_and_b64 vcc, exec, s[10:11]
	v_lshl_add_u32 v15, v15, 5, s63
	s_cbranch_vccnz .LBB0_382
	ds_read_b128 v[84:87], v15 offset:40960
	ds_read_b128 v[88:91], v15 offset:40976
	s_waitcnt lgkmcnt(0)
	v_ashrrev_i32_e32 v84, 6, v84
	v_ashrrev_i32_e32 v85, 6, v85
	v_cmp_le_i32_e32 vcc, v84, v215
	v_ashrrev_i32_e32 v84, 6, v86
	s_nop 1
	v_cndmask_b32_e32 v96, v212, v96, vcc
	v_cmp_le_i32_e32 vcc, v85, v215
	s_nop 1
	v_cndmask_b32_e32 v97, v212, v97, vcc
	v_cmp_le_i32_e32 vcc, v84, v215
	v_ashrrev_i32_e32 v84, 6, v87
	s_nop 0
	v_cndmask_b32_e32 v98, v212, v98, vcc
	v_cmp_le_i32_e32 vcc, v84, v215
	v_ashrrev_i32_e32 v84, 6, v88
	v_ashrrev_i32_e32 v88, 6, v91
	v_cndmask_b32_e32 v99, v212, v99, vcc
	v_cmp_le_i32_e32 vcc, v84, v215
	v_ashrrev_i32_e32 v84, 6, v89
	s_nop 0
	v_cndmask_b32_e32 v100, v212, v100, vcc
	v_cmp_le_i32_e32 vcc, v84, v215
	v_ashrrev_i32_e32 v84, 6, v90
	s_nop 0
	v_cndmask_b32_e32 v101, v212, v101, vcc
	v_cmp_le_i32_e32 vcc, v84, v215
	ds_read_b128 v[84:87], v15 offset:41024
	s_nop 0
	v_cndmask_b32_e32 v102, v212, v102, vcc
	v_cmp_le_i32_e32 vcc, v88, v215
	ds_read_b128 v[88:91], v15 offset:41040
	s_waitcnt lgkmcnt(0)
	v_ashrrev_i32_e32 v84, 6, v84
	v_cndmask_b32_e32 v103, v212, v103, vcc
	v_cmp_le_i32_e32 vcc, v84, v215
	v_ashrrev_i32_e32 v84, 6, v85
	s_nop 0
	v_cndmask_b32_e32 v104, v212, v104, vcc
	v_cmp_le_i32_e32 vcc, v84, v215
	v_ashrrev_i32_e32 v84, 6, v86
	s_nop 0
	v_cndmask_b32_e32 v105, v212, v105, vcc
	v_cmp_le_i32_e32 vcc, v84, v215
	v_ashrrev_i32_e32 v84, 6, v87
	s_nop 0
	v_cndmask_b32_e32 v106, v212, v106, vcc
	v_cmp_le_i32_e32 vcc, v84, v215
	v_ashrrev_i32_e32 v84, 6, v88
	s_nop 0
	v_cndmask_b32_e32 v107, v212, v107, vcc
	v_cmp_le_i32_e32 vcc, v84, v215
	v_ashrrev_i32_e32 v84, 6, v89
	s_nop 0
	v_cndmask_b32_e32 v108, v212, v108, vcc
	v_cmp_le_i32_e32 vcc, v84, v215
	v_ashrrev_i32_e32 v84, 6, v90
	s_nop 0
	v_cndmask_b32_e32 v109, v212, v109, vcc
	v_cmp_le_i32_e32 vcc, v84, v215
	v_ashrrev_i32_e32 v84, 6, v91
	s_nop 0
	v_cndmask_b32_e32 v110, v212, v110, vcc
	v_cmp_le_i32_e32 vcc, v84, v215
	s_nop 1
	v_cndmask_b32_e32 v111, v212, v111, vcc

; #define GLDS16(g, l) __builtin_amdgcn_global_load_lds((const unsigned*)(g), (unsigned*)(l), 16, 0, 0)
; #define GLDS4(g, l) __builtin_amdgcn_global_load_lds((const unsigned*)(g), (unsigned*)(l), 4, 0, 0)
; DI int tid_pinned() { int t = threadIdx.x; asm volatile("" : "+v"(t)); return t; }
; template <bool DIFF>
; DI void attn_phase(const AttnArgs& a, char* lds) {
;     ...
;       if (nxt) {
;         const int t2 = tid_pinned();
;         const u32 kofs = KOFS(t2), vofs = VOFS(t2);
;         const u32 ko2 = kofs + (u32)(t + 1) * 64u * (u32)a.ldk;
; #pragma unroll
;         for (int i = 0; i < NKR; ++i) GLDS16(a.K + ko2 + i * 64, nb + wave * 1024 + 8192 * i);
;         const u32 vo2 = vofs + (u32)(t + 1) * (u32)(DV * 64);
; #pragma unroll
;         for (int i = 0; i < NVR; ++i) GLDS16(a.VT + vo2 + i * 4096, nb + KBYTES + wave * 1024 + 8192 * i);
;         if (wave == 0) { const int l4 = (t + 1) * 64 + (t2 & 63); GLDS4(a.pos + l4, nb + KBYTES + VBYTES); GLDS4(a.posf + l4, nb + KBYTES + VBYTES + 256); }
;       }
.Lmla_slow:
	s_cmp_ge_i32 s53, s0
	s_cbranch_scc1 .LBB0_385
	v_mov_b32_e32 v2, v208
	v_lshrrev_b32_e32 v0, 4, v2
	v_xor_b32_e32 v0, v0, v2
	v_ashrrev_i32_e32 v3, 3, v2
	v_lshlrev_b32_e32 v0, 3, v0
	v_and_b32_e32 v8, 56, v0
	v_add_u32_e32 v0, s52, v3
	v_mul_lo_u32 v0, v0, s76
	v_add_u32_e32 v0, s4, v0
	v_or_b32_e32 v0, v0, v8
	v_lshl_add_u64 v[4:5], v[0:1], 1, s[14:15]
	s_mov_b32 m0, s88
	v_lshl_add_u64 v[6:7], v[4:5], 0, s[16:17]
	global_load_lds_dwordx4 v[4:5], off
	s_add_i32 m0, s88, 0x2000
	v_lshl_or_b32 v0, v3, 6, v8
	global_load_lds_dwordx4 v[6:7], off
	v_lshl_add_u64 v[4:5], v[4:5], 0, s[18:19]
	s_add_i32 m0, s88, 0x4000
	v_add_u32_e32 v0, s5, v0
	global_load_lds_dwordx4 v[4:5], off
	s_add_i32 m0, s88, 0x6000
	v_lshl_add_u64 v[4:5], v[0:1], 1, s[40:41]
	global_load_lds_dwordx4 v[4:5], off
	v_lshl_add_u64 v[4:5], v[4:5], 0, s[68:69]
	s_add_i32 m0, s88, 0x8000
	s_and_b64 vcc, exec, s[8:9]
	global_load_lds_dwordx4 v[4:5], off
	s_cbranch_vccnz .LBB0_385
	v_and_b32_e32 v0, 63, v2
	v_add_u32_e32 v2, s52, v0
	v_ashrrev_i32_e32 v3, 31, v2
	v_lshlrev_b64 v[2:3], 2, v[2:3]
	v_lshl_add_u64 v[4:5], s[48:49], 0, v[2:3]
	s_add_i32 m0, s85, 0xa000
	v_lshl_add_u64 v[2:3], s[38:39], 0, v[2:3]
	global_load_lds_dword v[2:3], off
	s_add_i32 m0, s85, 0xa100
	s_nop 0
	global_load_lds_dword v[4:5], off
	s_branch .LBB0_385
